# cmp_item main loop double-buffered: next round's 16 weight fragments requested before the current round's MFMAs (two register sets, counted waits)
# speedup vs baseline: 1.0019x; 1.0019x over previous
.LBB0_794:
	s_or_b64 exec, exec, s[28:29]
	s_ashr_i32 s18, s35, 6
	v_and_b32_e32 v29, 15, v4
	s_and_b64 s[12:13], s[26:27], exec
	v_lshl_or_b32 v20, s18, 5, v29
	s_mov_b32 s12, 0x2260000
	v_ashrrev_i32_e32 v21, 31, v20
	v_bfe_u32 v19, v4, 4, 2
	s_cselect_b32 s28, s12, 0x2360000
	s_mov_b32 s29, 0
	v_lshlrev_b64 v[2:3], 12, v[20:21]
	v_lshlrev_b32_e32 v18, 4, v19
	v_lshl_add_u64 v[2:3], s[28:29], 0, v[2:3]
	v_or_b32_e32 v2, v2, v18
	v_mov_b32_e32 v14, 0
	v_add_u32_e32 v0, 0, v18
	v_lshl_add_u64 v[22:23], s[66:67], 0, v[2:3]
	s_mov_b32 s12, 3
	s_mov_b64 s[30:31], 0
	v_mov_b32_e32 v15, v14
	v_mov_b32_e32 v16, v14
	v_mov_b32_e32 v17, v14
	v_mov_b32_e32 v6, v14
	v_mov_b32_e32 v7, v14
	v_mov_b32_e32 v8, v14
	v_mov_b32_e32 v9, v14
	v_mov_b32_e32 v10, v14
	v_mov_b32_e32 v11, v14
	v_mov_b32_e32 v12, v14
	v_mov_b32_e32 v13, v14
	v_mov_b32_e32 v2, v14
	v_mov_b32_e32 v3, v14
	v_mov_b32_e32 v4, v14
	v_mov_b32_e32 v5, v14
	s_waitcnt lgkmcnt(0)
	s_barrier
	v_lshl_add_u64 v[26:27], v[22:23], 0, s[30:31]
	s_mov_b32 s18, 0x408000
	v_add_co_u32_e32 v24, vcc, s18, v26
	s_mov_b32 s18, 0x418000
	s_nop 0
	v_addc_co_u32_e32 v25, vcc, 0, v27, vcc
	v_add_co_u32_e32 v26, vcc, s18, v26
	s_nop 1
	v_addc_co_u32_e32 v27, vcc, 0, v27, vcc
	global_load_dwordx4 v[70:73], v[24:25], off offset:1024
	global_load_dwordx4 v[74:77], v[26:27], off offset:1024
	global_load_dwordx4 v[78:81], v[24:25], off offset:1088
	global_load_dwordx4 v[82:85], v[26:27], off offset:1088
	global_load_dwordx4 v[86:89], v[24:25], off offset:1152
	global_load_dwordx4 v[90:93], v[26:27], off offset:1152
	global_load_dwordx4 v[94:97], v[24:25], off offset:1216
	global_load_dwordx4 v[98:101], v[26:27], off offset:1216
	global_load_dwordx4 v[102:105], v[24:25], off offset:1280
	global_load_dwordx4 v[106:109], v[26:27], off offset:1280
	global_load_dwordx4 v[110:113], v[24:25], off offset:1344
	global_load_dwordx4 v[114:117], v[26:27], off offset:1344
	global_load_dwordx4 v[118:121], v[24:25], off offset:1408
	global_load_dwordx4 v[122:125], v[26:27], off offset:1408
	global_load_dwordx4 v[126:129], v[24:25], off offset:1472
	global_load_dwordx4 v[130:133], v[26:27], off offset:1472
.LBB0_795:
	s_add_u32 s30, s30, 0x200
	s_addc_u32 s31, s31, 0
	v_lshl_add_u64 v[26:27], v[22:23], 0, s[30:31]
	s_mov_b32 s18, 0x408000
	v_add_co_u32_e32 v24, vcc, s18, v26
	s_mov_b32 s18, 0x418000
	s_nop 0
	v_addc_co_u32_e32 v25, vcc, 0, v27, vcc
	v_add_co_u32_e32 v26, vcc, s18, v26
	s_nop 1
	v_addc_co_u32_e32 v27, vcc, 0, v27, vcc
	global_load_dwordx4 v[204:207], v[24:25], off offset:1024
	global_load_dwordx4 v[208:211], v[26:27], off offset:1024
	global_load_dwordx4 v[212:215], v[24:25], off offset:1088
	global_load_dwordx4 v[216:219], v[26:27], off offset:1088
	global_load_dwordx4 v[220:223], v[24:25], off offset:1152
	global_load_dwordx4 v[224:227], v[26:27], off offset:1152
	global_load_dwordx4 v[228:231], v[24:25], off offset:1216
	global_load_dwordx4 v[232:235], v[26:27], off offset:1216
	global_load_dwordx4 v[236:239], v[24:25], off offset:1280
	global_load_dwordx4 v[240:243], v[26:27], off offset:1280
	global_load_dwordx4 v[244:247], v[24:25], off offset:1344
	global_load_dwordx4 v[134:137], v[26:27], off offset:1344
	global_load_dwordx4 v[138:141], v[24:25], off offset:1408
	global_load_dwordx4 v[142:145], v[26:27], off offset:1408
	global_load_dwordx4 v[162:165], v[24:25], off offset:1472
	global_load_dwordx4 v[166:169], v[26:27], off offset:1472
	s_lshr_b32 s18, s29, 5
	v_add_u32_e32 v28, s18, v29
	s_add_i32 s29, s29, 8
	s_add_i32 s13, s12, -3
	s_and_b32 s13, s13, 12
	v_mad_u64_u32 v[38:39], s[18:19], s13, 34, v[28:29]
	v_mad_u64_u32 v[46:47], s[18:19], v38, s0, v[0:1]
	ds_read_b128 v[38:41], v46
	ds_read_b128 v[42:45], v46 offset:2304
	s_waitcnt vmcnt(30) lgkmcnt(1)
	v_mfma_f32_16x16x32_bf16 v[14:17], v[38:41], v[70:73], v[14:17]
	v_mfma_f32_16x16x32_bf16 v[6:9], v[38:41], v[74:77], v[6:9]
	s_waitcnt lgkmcnt(0)
	v_mfma_f32_16x16x32_bf16 v[10:13], v[42:45], v[70:73], v[10:13]
	v_mfma_f32_16x16x32_bf16 v[2:5], v[42:45], v[74:77], v[2:5]
	ds_read_b128 v[38:41], v46 offset:64
	ds_read_b128 v[42:45], v46 offset:2368
	s_waitcnt vmcnt(28) lgkmcnt(1)
	v_mfma_f32_16x16x32_bf16 v[14:17], v[38:41], v[78:81], v[14:17]
	v_mfma_f32_16x16x32_bf16 v[6:9], v[38:41], v[82:85], v[6:9]
	s_waitcnt lgkmcnt(0)
	v_mfma_f32_16x16x32_bf16 v[10:13], v[42:45], v[78:81], v[10:13]
	v_mfma_f32_16x16x32_bf16 v[2:5], v[42:45], v[82:85], v[2:5]
	s_add_i32 s13, s12, -2
	s_and_b32 s13, s13, 13
	v_mad_u64_u32 v[38:39], s[18:19], s13, 34, v[28:29]
	v_mad_u64_u32 v[46:47], s[18:19], v38, s0, v[0:1]
	ds_read_b128 v[38:41], v46
	ds_read_b128 v[42:45], v46 offset:2304
	s_waitcnt vmcnt(26) lgkmcnt(1)
	v_mfma_f32_16x16x32_bf16 v[14:17], v[38:41], v[86:89], v[14:17]
	v_mfma_f32_16x16x32_bf16 v[6:9], v[38:41], v[90:93], v[6:9]
	s_waitcnt lgkmcnt(0)
	v_mfma_f32_16x16x32_bf16 v[10:13], v[42:45], v[86:89], v[10:13]
	v_mfma_f32_16x16x32_bf16 v[2:5], v[42:45], v[90:93], v[2:5]
	ds_read_b128 v[38:41], v46 offset:64
	ds_read_b128 v[42:45], v46 offset:2368
	s_waitcnt vmcnt(24) lgkmcnt(1)
	v_mfma_f32_16x16x32_bf16 v[14:17], v[38:41], v[94:97], v[14:17]
	v_mfma_f32_16x16x32_bf16 v[6:9], v[38:41], v[98:101], v[6:9]
	s_waitcnt lgkmcnt(0)
	v_mfma_f32_16x16x32_bf16 v[10:13], v[42:45], v[94:97], v[10:13]
	v_mfma_f32_16x16x32_bf16 v[2:5], v[42:45], v[98:101], v[2:5]
	s_add_i32 s13, s12, -1
	s_and_b32 s13, s13, 14
	v_mad_u64_u32 v[38:39], s[18:19], s13, 34, v[28:29]
	v_mad_u64_u32 v[46:47], s[18:19], v38, s0, v[0:1]
	ds_read_b128 v[38:41], v46
	ds_read_b128 v[42:45], v46 offset:2304
	s_waitcnt vmcnt(22) lgkmcnt(1)
	v_mfma_f32_16x16x32_bf16 v[14:17], v[38:41], v[102:105], v[14:17]
	v_mfma_f32_16x16x32_bf16 v[6:9], v[38:41], v[106:109], v[6:9]
	s_waitcnt lgkmcnt(0)
	v_mfma_f32_16x16x32_bf16 v[10:13], v[42:45], v[102:105], v[10:13]
	v_mfma_f32_16x16x32_bf16 v[2:5], v[42:45], v[106:109], v[2:5]
	ds_read_b128 v[38:41], v46 offset:64
	ds_read_b128 v[42:45], v46 offset:2368
	s_waitcnt vmcnt(20) lgkmcnt(1)
	v_mfma_f32_16x16x32_bf16 v[14:17], v[38:41], v[110:113], v[14:17]
	v_mfma_f32_16x16x32_bf16 v[6:9], v[38:41], v[114:117], v[6:9]
	s_waitcnt lgkmcnt(0)
	v_mfma_f32_16x16x32_bf16 v[10:13], v[42:45], v[110:113], v[10:13]
	v_mfma_f32_16x16x32_bf16 v[2:5], v[42:45], v[114:117], v[2:5]
	s_and_b32 s13, s12, 15
	v_mad_u64_u32 v[38:39], s[18:19], s13, 34, v[28:29]
	v_mad_u64_u32 v[46:47], s[18:19], v38, s0, v[0:1]
	ds_read_b128 v[38:41], v46
	ds_read_b128 v[42:45], v46 offset:2304
	s_waitcnt vmcnt(18) lgkmcnt(1)
	v_mfma_f32_16x16x32_bf16 v[14:17], v[38:41], v[118:121], v[14:17]
	v_mfma_f32_16x16x32_bf16 v[6:9], v[38:41], v[122:125], v[6:9]
	s_waitcnt lgkmcnt(0)
	v_mfma_f32_16x16x32_bf16 v[10:13], v[42:45], v[118:121], v[10:13]
	v_mfma_f32_16x16x32_bf16 v[2:5], v[42:45], v[122:125], v[2:5]
	ds_read_b128 v[38:41], v46 offset:64
	ds_read_b128 v[42:45], v46 offset:2368
	s_waitcnt vmcnt(16) lgkmcnt(1)
	v_mfma_f32_16x16x32_bf16 v[14:17], v[38:41], v[126:129], v[14:17]
	v_mfma_f32_16x16x32_bf16 v[6:9], v[38:41], v[130:133], v[6:9]
	s_waitcnt lgkmcnt(0)
	v_mfma_f32_16x16x32_bf16 v[10:13], v[42:45], v[126:129], v[10:13]
	v_mfma_f32_16x16x32_bf16 v[2:5], v[42:45], v[130:133], v[2:5]
	s_add_i32 s12, s12, 4
	s_add_u32 s30, s30, 0x200
	s_addc_u32 s31, s31, 0
	s_cmpk_eq_i32 s30, 0x1000
	s_cbranch_scc1 .Lcmp_last
	v_lshl_add_u64 v[26:27], v[22:23], 0, s[30:31]
	s_mov_b32 s18, 0x408000
	v_add_co_u32_e32 v24, vcc, s18, v26
	s_mov_b32 s18, 0x418000
	s_nop 0
	v_addc_co_u32_e32 v25, vcc, 0, v27, vcc
	v_add_co_u32_e32 v26, vcc, s18, v26
	s_nop 1
	v_addc_co_u32_e32 v27, vcc, 0, v27, vcc
	global_load_dwordx4 v[70:73], v[24:25], off offset:1024
	global_load_dwordx4 v[74:77], v[26:27], off offset:1024
	global_load_dwordx4 v[78:81], v[24:25], off offset:1088
	global_load_dwordx4 v[82:85], v[26:27], off offset:1088
	global_load_dwordx4 v[86:89], v[24:25], off offset:1152
	global_load_dwordx4 v[90:93], v[26:27], off offset:1152
	global_load_dwordx4 v[94:97], v[24:25], off offset:1216
	global_load_dwordx4 v[98:101], v[26:27], off offset:1216
	global_load_dwordx4 v[102:105], v[24:25], off offset:1280
	global_load_dwordx4 v[106:109], v[26:27], off offset:1280
	global_load_dwordx4 v[110:113], v[24:25], off offset:1344
	global_load_dwordx4 v[114:117], v[26:27], off offset:1344
	global_load_dwordx4 v[118:121], v[24:25], off offset:1408
	global_load_dwordx4 v[122:125], v[26:27], off offset:1408
	global_load_dwordx4 v[126:129], v[24:25], off offset:1472
	global_load_dwordx4 v[130:133], v[26:27], off offset:1472
	s_lshr_b32 s18, s29, 5
	v_add_u32_e32 v28, s18, v29
	s_add_i32 s29, s29, 8
	s_add_i32 s13, s12, -3
	s_and_b32 s13, s13, 12
	v_mad_u64_u32 v[38:39], s[18:19], s13, 34, v[28:29]
	v_mad_u64_u32 v[46:47], s[18:19], v38, s0, v[0:1]
	ds_read_b128 v[38:41], v46
	ds_read_b128 v[42:45], v46 offset:2304
	s_waitcnt vmcnt(30) lgkmcnt(1)
	v_mfma_f32_16x16x32_bf16 v[14:17], v[38:41], v[204:207], v[14:17]
	v_mfma_f32_16x16x32_bf16 v[6:9], v[38:41], v[208:211], v[6:9]
	s_waitcnt lgkmcnt(0)
	v_mfma_f32_16x16x32_bf16 v[10:13], v[42:45], v[204:207], v[10:13]
	v_mfma_f32_16x16x32_bf16 v[2:5], v[42:45], v[208:211], v[2:5]
	ds_read_b128 v[38:41], v46 offset:64
	ds_read_b128 v[42:45], v46 offset:2368
	s_waitcnt vmcnt(28) lgkmcnt(1)
	v_mfma_f32_16x16x32_bf16 v[14:17], v[38:41], v[212:215], v[14:17]
	v_mfma_f32_16x16x32_bf16 v[6:9], v[38:41], v[216:219], v[6:9]
	s_waitcnt lgkmcnt(0)
	v_mfma_f32_16x16x32_bf16 v[10:13], v[42:45], v[212:215], v[10:13]
	v_mfma_f32_16x16x32_bf16 v[2:5], v[42:45], v[216:219], v[2:5]
	s_add_i32 s13, s12, -2
	s_and_b32 s13, s13, 13
	v_mad_u64_u32 v[38:39], s[18:19], s13, 34, v[28:29]
	v_mad_u64_u32 v[46:47], s[18:19], v38, s0, v[0:1]
	ds_read_b128 v[38:41], v46
	ds_read_b128 v[42:45], v46 offset:2304
	s_waitcnt vmcnt(26) lgkmcnt(1)
	v_mfma_f32_16x16x32_bf16 v[14:17], v[38:41], v[220:223], v[14:17]
	v_mfma_f32_16x16x32_bf16 v[6:9], v[38:41], v[224:227], v[6:9]
	s_waitcnt lgkmcnt(0)
	v_mfma_f32_16x16x32_bf16 v[10:13], v[42:45], v[220:223], v[10:13]
	v_mfma_f32_16x16x32_bf16 v[2:5], v[42:45], v[224:227], v[2:5]
	ds_read_b128 v[38:41], v46 offset:64
	ds_read_b128 v[42:45], v46 offset:2368
	s_waitcnt vmcnt(24) lgkmcnt(1)
	v_mfma_f32_16x16x32_bf16 v[14:17], v[38:41], v[228:231], v[14:17]
	v_mfma_f32_16x16x32_bf16 v[6:9], v[38:41], v[232:235], v[6:9]
	s_waitcnt lgkmcnt(0)
	v_mfma_f32_16x16x32_bf16 v[10:13], v[42:45], v[228:231], v[10:13]
	v_mfma_f32_16x16x32_bf16 v[2:5], v[42:45], v[232:235], v[2:5]
	s_add_i32 s13, s12, -1
	s_and_b32 s13, s13, 14
	v_mad_u64_u32 v[38:39], s[18:19], s13, 34, v[28:29]
	v_mad_u64_u32 v[46:47], s[18:19], v38, s0, v[0:1]
	ds_read_b128 v[38:41], v46
	ds_read_b128 v[42:45], v46 offset:2304
	s_waitcnt vmcnt(22) lgkmcnt(1)
	v_mfma_f32_16x16x32_bf16 v[14:17], v[38:41], v[236:239], v[14:17]
	v_mfma_f32_16x16x32_bf16 v[6:9], v[38:41], v[240:243], v[6:9]
	s_waitcnt lgkmcnt(0)
	v_mfma_f32_16x16x32_bf16 v[10:13], v[42:45], v[236:239], v[10:13]
	v_mfma_f32_16x16x32_bf16 v[2:5], v[42:45], v[240:243], v[2:5]
	ds_read_b128 v[38:41], v46 offset:64
	ds_read_b128 v[42:45], v46 offset:2368
	s_waitcnt vmcnt(20) lgkmcnt(1)
	v_mfma_f32_16x16x32_bf16 v[14:17], v[38:41], v[244:247], v[14:17]
	v_mfma_f32_16x16x32_bf16 v[6:9], v[38:41], v[134:137], v[6:9]
	s_waitcnt lgkmcnt(0)
	v_mfma_f32_16x16x32_bf16 v[10:13], v[42:45], v[244:247], v[10:13]
	v_mfma_f32_16x16x32_bf16 v[2:5], v[42:45], v[134:137], v[2:5]
	s_and_b32 s13, s12, 15
	v_mad_u64_u32 v[38:39], s[18:19], s13, 34, v[28:29]
	v_mad_u64_u32 v[46:47], s[18:19], v38, s0, v[0:1]
	ds_read_b128 v[38:41], v46
	ds_read_b128 v[42:45], v46 offset:2304
	s_waitcnt vmcnt(18) lgkmcnt(1)
	v_mfma_f32_16x16x32_bf16 v[14:17], v[38:41], v[138:141], v[14:17]
	v_mfma_f32_16x16x32_bf16 v[6:9], v[38:41], v[142:145], v[6:9]
	s_waitcnt lgkmcnt(0)
	v_mfma_f32_16x16x32_bf16 v[10:13], v[42:45], v[138:141], v[10:13]
	v_mfma_f32_16x16x32_bf16 v[2:5], v[42:45], v[142:145], v[2:5]
	ds_read_b128 v[38:41], v46 offset:64
	ds_read_b128 v[42:45], v46 offset:2368
	s_waitcnt vmcnt(16) lgkmcnt(1)
	v_mfma_f32_16x16x32_bf16 v[14:17], v[38:41], v[162:165], v[14:17]
	v_mfma_f32_16x16x32_bf16 v[6:9], v[38:41], v[166:169], v[6:9]
	s_waitcnt lgkmcnt(0)
	v_mfma_f32_16x16x32_bf16 v[10:13], v[42:45], v[162:165], v[10:13]
	v_mfma_f32_16x16x32_bf16 v[2:5], v[42:45], v[166:169], v[2:5]
	s_add_i32 s12, s12, 4
	s_branch .LBB0_795
.Lcmp_last:
	s_lshr_b32 s18, s29, 5
	v_add_u32_e32 v28, s18, v29
	s_add_i32 s29, s29, 8
	s_add_i32 s13, s12, -3
	s_and_b32 s13, s13, 12
	v_mad_u64_u32 v[38:39], s[18:19], s13, 34, v[28:29]
	v_mad_u64_u32 v[46:47], s[18:19], v38, s0, v[0:1]
	ds_read_b128 v[38:41], v46
	ds_read_b128 v[42:45], v46 offset:2304
	s_waitcnt vmcnt(14) lgkmcnt(1)
	v_mfma_f32_16x16x32_bf16 v[14:17], v[38:41], v[204:207], v[14:17]
	v_mfma_f32_16x16x32_bf16 v[6:9], v[38:41], v[208:211], v[6:9]
	s_waitcnt lgkmcnt(0)
	v_mfma_f32_16x16x32_bf16 v[10:13], v[42:45], v[204:207], v[10:13]
	v_mfma_f32_16x16x32_bf16 v[2:5], v[42:45], v[208:211], v[2:5]
	ds_read_b128 v[38:41], v46 offset:64
	ds_read_b128 v[42:45], v46 offset:2368
	s_waitcnt vmcnt(12) lgkmcnt(1)
	v_mfma_f32_16x16x32_bf16 v[14:17], v[38:41], v[212:215], v[14:17]
	v_mfma_f32_16x16x32_bf16 v[6:9], v[38:41], v[216:219], v[6:9]
	s_waitcnt lgkmcnt(0)
	v_mfma_f32_16x16x32_bf16 v[10:13], v[42:45], v[212:215], v[10:13]
	v_mfma_f32_16x16x32_bf16 v[2:5], v[42:45], v[216:219], v[2:5]
	s_add_i32 s13, s12, -2
	s_and_b32 s13, s13, 13
	v_mad_u64_u32 v[38:39], s[18:19], s13, 34, v[28:29]
	v_mad_u64_u32 v[46:47], s[18:19], v38, s0, v[0:1]
	ds_read_b128 v[38:41], v46
	ds_read_b128 v[42:45], v46 offset:2304
	s_waitcnt vmcnt(10) lgkmcnt(1)
	v_mfma_f32_16x16x32_bf16 v[14:17], v[38:41], v[220:223], v[14:17]
	v_mfma_f32_16x16x32_bf16 v[6:9], v[38:41], v[224:227], v[6:9]
	s_waitcnt lgkmcnt(0)
	v_mfma_f32_16x16x32_bf16 v[10:13], v[42:45], v[220:223], v[10:13]
	v_mfma_f32_16x16x32_bf16 v[2:5], v[42:45], v[224:227], v[2:5]
	ds_read_b128 v[38:41], v46 offset:64
	ds_read_b128 v[42:45], v46 offset:2368
	s_waitcnt vmcnt(8) lgkmcnt(1)
	v_mfma_f32_16x16x32_bf16 v[14:17], v[38:41], v[228:231], v[14:17]
	v_mfma_f32_16x16x32_bf16 v[6:9], v[38:41], v[232:235], v[6:9]
	s_waitcnt lgkmcnt(0)
	v_mfma_f32_16x16x32_bf16 v[10:13], v[42:45], v[228:231], v[10:13]
	v_mfma_f32_16x16x32_bf16 v[2:5], v[42:45], v[232:235], v[2:5]
	s_add_i32 s13, s12, -1
	s_and_b32 s13, s13, 14
	v_mad_u64_u32 v[38:39], s[18:19], s13, 34, v[28:29]
	v_mad_u64_u32 v[46:47], s[18:19], v38, s0, v[0:1]
	ds_read_b128 v[38:41], v46
	ds_read_b128 v[42:45], v46 offset:2304
	s_waitcnt vmcnt(6) lgkmcnt(1)
	v_mfma_f32_16x16x32_bf16 v[14:17], v[38:41], v[236:239], v[14:17]
	v_mfma_f32_16x16x32_bf16 v[6:9], v[38:41], v[240:243], v[6:9]
	s_waitcnt lgkmcnt(0)
	v_mfma_f32_16x16x32_bf16 v[10:13], v[42:45], v[236:239], v[10:13]
	v_mfma_f32_16x16x32_bf16 v[2:5], v[42:45], v[240:243], v[2:5]
	ds_read_b128 v[38:41], v46 offset:64
	ds_read_b128 v[42:45], v46 offset:2368
	s_waitcnt vmcnt(4) lgkmcnt(1)
	v_mfma_f32_16x16x32_bf16 v[14:17], v[38:41], v[244:247], v[14:17]
	v_mfma_f32_16x16x32_bf16 v[6:9], v[38:41], v[134:137], v[6:9]
	s_waitcnt lgkmcnt(0)
	v_mfma_f32_16x16x32_bf16 v[10:13], v[42:45], v[244:247], v[10:13]
	v_mfma_f32_16x16x32_bf16 v[2:5], v[42:45], v[134:137], v[2:5]
	s_and_b32 s13, s12, 15
	v_mad_u64_u32 v[38:39], s[18:19], s13, 34, v[28:29]
	v_mad_u64_u32 v[46:47], s[18:19], v38, s0, v[0:1]
	ds_read_b128 v[38:41], v46
	ds_read_b128 v[42:45], v46 offset:2304
	s_waitcnt vmcnt(2) lgkmcnt(1)
	v_mfma_f32_16x16x32_bf16 v[14:17], v[38:41], v[138:141], v[14:17]
	v_mfma_f32_16x16x32_bf16 v[6:9], v[38:41], v[142:145], v[6:9]
	s_waitcnt lgkmcnt(0)
	v_mfma_f32_16x16x32_bf16 v[10:13], v[42:45], v[138:141], v[10:13]
	v_mfma_f32_16x16x32_bf16 v[2:5], v[42:45], v[142:145], v[2:5]
	ds_read_b128 v[38:41], v46 offset:64
	ds_read_b128 v[42:45], v46 offset:2368
	s_waitcnt vmcnt(0) lgkmcnt(1)
	v_mfma_f32_16x16x32_bf16 v[14:17], v[38:41], v[162:165], v[14:17]
	v_mfma_f32_16x16x32_bf16 v[6:9], v[38:41], v[166:169], v[6:9]
	s_waitcnt lgkmcnt(0)
	v_mfma_f32_16x16x32_bf16 v[10:13], v[42:45], v[162:165], v[10:13]
	v_mfma_f32_16x16x32_bf16 v[2:5], v[42:45], v[166:169], v[2:5]
	s_add_i32 s12, s12, 4
	s_lshl_b32 s4, s4, 11
	s_lshl_b32 s28, s5, 5
	s_ashr_i32 s5, s4, 31
	s_lshl_b64 s[4:5], s[4:5], 2
	s_add_u32 s4, s79, s4
	s_addc_u32 s5, s86, s5
	v_lshl_add_u64 v[24:25], v[20:21], 2, s[4:5]
	global_load_dword v0, v[24:25], off
	global_load_dword v21, v[24:25], off offset:1024
	s_movk_i32 s4, 0x1000
	v_add_co_u32_e32 v22, vcc, s4, v24
	v_readlane_b32 s18, v250, 42
	s_nop 0
	v_addc_co_u32_e32 v23, vcc, 0, v25, vcc
	s_movk_i32 s4, 0x840
	v_lshlrev_b32_e32 v20, 1, v20
	v_lshlrev_b32_e32 v26, 2, v19
	s_waitcnt vmcnt(1)
	v_add_f32_e32 v0, 0, v0
	s_waitcnt vmcnt(0)
	v_add_f32_e32 v0, v0, v21
	global_load_dword v21, v[24:25], off offset:2048
	s_waitcnt vmcnt(0)
	v_add_f32_e32 v0, v0, v21
	global_load_dword v21, v[24:25], off offset:3072
	s_waitcnt vmcnt(0)
	v_add_f32_e32 v0, v0, v21
	global_load_dword v21, v[22:23], off
	s_waitcnt vmcnt(0)
	v_add_f32_e32 v0, v0, v21
	global_load_dword v21, v[22:23], off offset:1024
	s_waitcnt vmcnt(0)
	v_add_f32_e32 v0, v0, v21
	global_load_dword v21, v[22:23], off offset:2048
	s_waitcnt vmcnt(0)
	v_add_f32_e32 v0, v0, v21
	global_load_dword v21, v[22:23], off offset:3072
	s_waitcnt vmcnt(0)
	v_add_f32_e32 v21, v0, v21
	v_add_f32_e32 v0, v14, v21
	v_mul_f32_e32 v14, 0x3d372713, v0
	v_mul_f32_e32 v14, v0, v14
	v_fma_f32 v14, v0, v14, v0
	v_mul_f32_e32 v14, 0x3fcc422a, v14
	v_mul_f32_e32 v14, 0xbfb8aa3b, v14
	v_exp_f32_e32 v14, v14
	v_add_f32_e32 v15, v15, v21
	v_add_f32_e32 v10, v10, v21
	v_add_f32_e32 v14, 1.0, v14
	v_rcp_f32_e32 v14, v14
	s_nop 0
	v_mul_f32_e32 v0, v0, v14
	v_mov_b32_e32 v14, s18
	v_mad_u32_u24 v14, v19, s4, v14
	v_cvt_pk_bf16_f32 v27, v0, s0
	v_add_u32_e32 v28, v14, v20
	ds_write_b16 v28, v27
	v_mul_f32_e32 v27, 0x3d372713, v15
	v_mul_f32_e32 v27, v15, v27
	v_fma_f32 v27, v15, v27, v15
	v_mul_f32_e32 v27, 0x3fcc422a, v27
	v_mul_f32_e32 v27, 0xbfb8aa3b, v27
	v_exp_f32_e32 v27, v27
	v_mul_u32_u24_e32 v0, 0x840, v19
	s_and_b64 s[4:5], s[26:27], exec
	s_mov_b32 s4, 0x2460000
	v_add_f32_e32 v27, 1.0, v27
	v_rcp_f32_e32 v27, v27
	s_cselect_b32 s4, s4, 0x2468000
	s_add_u32 s12, s61, s4
	s_addc_u32 s13, s78, 0
	v_mul_f32_e32 v15, v15, v27
	v_cvt_pk_bf16_f32 v15, v15, s0
	ds_write_b16 v28, v15 offset:528
	v_add_f32_e32 v15, v16, v21
	v_mul_f32_e32 v16, 0x3d372713, v15
	v_mul_f32_e32 v16, v15, v16
	v_fma_f32 v16, v15, v16, v15
	v_mul_f32_e32 v16, 0x3fcc422a, v16
	v_mul_f32_e32 v16, 0xbfb8aa3b, v16
	v_exp_f32_e32 v16, v16
	s_ashr_i32 s5, s35, 4
	s_and_b32 s26, s5, -16
	s_movk_i32 s5, 0x108
	v_add_f32_e32 v16, 1.0, v16
	v_rcp_f32_e32 v16, v16
	s_bfe_u32 s4, s35, 0x20006
	s_and_b64 vcc, exec, s[10:11]
	v_mul_f32_e32 v15, v15, v16
	v_cvt_pk_bf16_f32 v15, v15, s0
	ds_write_b16 v28, v15 offset:1056
	v_add_f32_e32 v15, v17, v21
	v_mul_f32_e32 v16, 0x3d372713, v15
	v_mul_f32_e32 v16, v15, v16
	v_fma_f32 v16, v15, v16, v15
	v_mul_f32_e32 v16, 0x3fcc422a, v16
	v_mul_f32_e32 v16, 0xbfb8aa3b, v16
	v_exp_f32_e32 v16, v16
	s_nop 0
	v_add_f32_e32 v16, 1.0, v16
	v_rcp_f32_e32 v16, v16
	s_nop 0
	v_mul_f32_e32 v15, v15, v16
	v_cvt_pk_bf16_f32 v15, v15, s0
	ds_write_b16 v28, v15 offset:1584
	v_mul_f32_e32 v15, 0x3d372713, v10
	v_mul_f32_e32 v15, v10, v15
	v_fma_f32 v15, v10, v15, v10
	v_mul_f32_e32 v15, 0x3fcc422a, v15
	v_mul_f32_e32 v15, 0xbfb8aa3b, v15
	v_exp_f32_e32 v15, v15
	s_nop 0
	v_add_f32_e32 v15, 1.0, v15
	v_rcp_f32_e32 v15, v15
	s_nop 0
	v_mul_f32_e32 v10, v10, v15
	v_cvt_pk_bf16_f32 v10, v10, s0
	ds_write_b16 v28, v10 offset:8448
	v_add_f32_e32 v10, v11, v21
	v_mul_f32_e32 v11, 0x3d372713, v10
	v_mul_f32_e32 v11, v10, v11
	v_fma_f32 v11, v10, v11, v10
	v_mul_f32_e32 v11, 0x3fcc422a, v11
	v_mul_f32_e32 v11, 0xbfb8aa3b, v11
	v_exp_f32_e32 v11, v11
	s_nop 0
	v_add_f32_e32 v11, 1.0, v11
	v_rcp_f32_e32 v11, v11
	s_nop 0
	v_mul_f32_e32 v10, v10, v11
	v_cvt_pk_bf16_f32 v10, v10, s0
	ds_write_b16 v28, v10 offset:8976
	v_add_f32_e32 v10, v12, v21
	v_mul_f32_e32 v11, 0x3d372713, v10
	v_mul_f32_e32 v11, v10, v11
	v_fma_f32 v11, v10, v11, v10
	v_mul_f32_e32 v11, 0x3fcc422a, v11
	v_mul_f32_e32 v11, 0xbfb8aa3b, v11
	v_exp_f32_e32 v11, v11
	s_nop 0
	v_add_f32_e32 v11, 1.0, v11
	v_rcp_f32_e32 v11, v11
	s_nop 0
	v_mul_f32_e32 v10, v10, v11
	v_cvt_pk_bf16_f32 v10, v10, s0
	ds_write_b16 v28, v10 offset:9504
	v_add_f32_e32 v10, v13, v21
	v_mul_f32_e32 v11, 0x3d372713, v10
	v_mul_f32_e32 v11, v10, v11
	v_fma_f32 v11, v10, v11, v10
	v_mul_f32_e32 v11, 0x3fcc422a, v11
	v_mul_f32_e32 v11, 0xbfb8aa3b, v11
	v_exp_f32_e32 v11, v11
	s_nop 0
	v_add_f32_e32 v11, 1.0, v11
	v_rcp_f32_e32 v11, v11
	s_nop 0
	v_mul_f32_e32 v10, v10, v11
	v_cvt_pk_bf16_f32 v10, v10, s0
	ds_write_b16 v28, v10 offset:10032
	global_load_dword v10, v[24:25], off offset:64
	global_load_dword v11, v[24:25], off offset:1088
	s_waitcnt vmcnt(1)
	v_add_f32_e32 v10, 0, v10
	s_waitcnt vmcnt(0)
	v_add_f32_e32 v10, v10, v11
	global_load_dword v11, v[24:25], off offset:2112
	s_waitcnt vmcnt(0)
	v_add_f32_e32 v10, v10, v11
	global_load_dword v11, v[24:25], off offset:3136
	s_waitcnt vmcnt(0)
	v_add_f32_e32 v10, v10, v11
	global_load_dword v11, v[22:23], off offset:64
	s_waitcnt vmcnt(0)
	v_add_f32_e32 v10, v10, v11
	global_load_dword v11, v[22:23], off offset:1088
	s_waitcnt vmcnt(0)
	v_add_f32_e32 v10, v10, v11
	global_load_dword v11, v[22:23], off offset:2112
	s_waitcnt vmcnt(0)
	v_add_f32_e32 v10, v10, v11
	global_load_dword v11, v[22:23], off offset:3136
	s_waitcnt vmcnt(0)
	v_add_f32_e32 v10, v10, v11
	v_add_f32_e32 v6, v6, v10
	v_mul_f32_e32 v12, 0x3d372713, v6
	v_mul_f32_e32 v12, v6, v12
	v_fma_f32 v12, v6, v12, v6
	v_mul_f32_e32 v12, 0x3fcc422a, v12
	v_mul_f32_e32 v12, 0xbfb8aa3b, v12
	v_exp_f32_e32 v12, v12
	v_or_b32_e32 v11, 32, v20
	v_add3_u32 v0, s18, v11, v0
	v_add_f32_e32 v2, v2, v10
	v_add_f32_e32 v12, 1.0, v12
	v_rcp_f32_e32 v12, v12
	s_nop 0
	v_mul_f32_e32 v6, v6, v12
	v_cvt_pk_bf16_f32 v6, v6, s0
	v_add_u32_e32 v12, v14, v11
	ds_write_b16 v12, v6
	v_add_f32_e32 v6, v7, v10
	v_mul_f32_e32 v7, 0x3d372713, v6
	v_mul_f32_e32 v7, v6, v7
	v_fma_f32 v7, v6, v7, v6
	v_mul_f32_e32 v7, 0x3fcc422a, v7
	v_mul_f32_e32 v7, 0xbfb8aa3b, v7
	v_exp_f32_e32 v7, v7
	s_nop 0
	v_add_f32_e32 v7, 1.0, v7
	v_rcp_f32_e32 v7, v7
	s_nop 0
	v_mul_f32_e32 v6, v6, v7
	v_cvt_pk_bf16_f32 v6, v6, s0
	ds_write_b16 v0, v6 offset:528
	v_add_f32_e32 v6, v8, v10
	v_mul_f32_e32 v7, 0x3d372713, v6
	v_mul_f32_e32 v7, v6, v7
	v_fma_f32 v7, v6, v7, v6
	v_mul_f32_e32 v7, 0x3fcc422a, v7
	v_mul_f32_e32 v7, 0xbfb8aa3b, v7
	v_exp_f32_e32 v7, v7
	s_nop 0
	v_add_f32_e32 v7, 1.0, v7
	v_rcp_f32_e32 v7, v7
	s_nop 0
	v_mul_f32_e32 v6, v6, v7
	v_cvt_pk_bf16_f32 v6, v6, s0
	ds_write_b16 v0, v6 offset:1056
	v_add_f32_e32 v6, v9, v10
	v_mul_f32_e32 v7, 0x3d372713, v6
	v_mul_f32_e32 v7, v6, v7
	v_fma_f32 v7, v6, v7, v6
	v_mul_f32_e32 v7, 0x3fcc422a, v7
	v_mul_f32_e32 v7, 0xbfb8aa3b, v7
	v_exp_f32_e32 v7, v7
	s_nop 0
	v_add_f32_e32 v7, 1.0, v7
	v_rcp_f32_e32 v7, v7
	s_nop 0
	v_mul_f32_e32 v6, v6, v7
	v_cvt_pk_bf16_f32 v6, v6, s0
	ds_write_b16 v0, v6 offset:1584
	v_mul_f32_e32 v6, 0x3d372713, v2
	v_mul_f32_e32 v6, v2, v6
	v_fma_f32 v6, v2, v6, v2
	v_mul_f32_e32 v6, 0x3fcc422a, v6
	v_mul_f32_e32 v6, 0xbfb8aa3b, v6
	v_exp_f32_e32 v6, v6
	s_nop 0
	v_add_f32_e32 v6, 1.0, v6
	v_rcp_f32_e32 v6, v6
	s_nop 0
	v_mul_f32_e32 v2, v2, v6
	v_cvt_pk_bf16_f32 v2, v2, s0
	ds_write_b16 v0, v2 offset:8448
	v_add_f32_e32 v2, v3, v10
	v_mul_f32_e32 v3, 0x3d372713, v2
	v_mul_f32_e32 v3, v2, v3
	v_fma_f32 v3, v2, v3, v2
	v_mul_f32_e32 v3, 0x3fcc422a, v3
	v_mul_f32_e32 v3, 0xbfb8aa3b, v3
	v_exp_f32_e32 v3, v3
	s_nop 0
	v_add_f32_e32 v3, 1.0, v3
	v_rcp_f32_e32 v3, v3
	s_nop 0
	v_mul_f32_e32 v2, v2, v3
	v_cvt_pk_bf16_f32 v2, v2, s0
	ds_write_b16 v0, v2 offset:8976
	v_add_f32_e32 v2, v4, v10
	v_mul_f32_e32 v3, 0x3d372713, v2
	v_mul_f32_e32 v3, v2, v3
	v_fma_f32 v3, v2, v3, v2
	v_mul_f32_e32 v3, 0x3fcc422a, v3
	v_mul_f32_e32 v3, 0xbfb8aa3b, v3
	v_exp_f32_e32 v3, v3
	s_nop 0
	v_add_f32_e32 v3, 1.0, v3
	v_rcp_f32_e32 v3, v3
	s_nop 0
	v_mul_f32_e32 v2, v2, v3
	v_cvt_pk_bf16_f32 v2, v2, s0
	ds_write_b16 v0, v2 offset:9504
	v_add_f32_e32 v2, v5, v10
	v_mul_f32_e32 v3, 0x3d372713, v2
	v_mul_f32_e32 v3, v2, v3
	v_fma_f32 v3, v2, v3, v2
	v_mul_f32_e32 v3, 0x3fcc422a, v3
	v_mul_f32_e32 v3, 0xbfb8aa3b, v3
	v_exp_f32_e32 v3, v3
	s_nop 0
	v_add_f32_e32 v3, 1.0, v3
	v_rcp_f32_e32 v3, v3
	s_nop 0
	v_mul_f32_e32 v2, v2, v3
	v_cvt_pk_bf16_f32 v2, v2, s0
	ds_write_b16 v0, v2 offset:10032
	v_or_b32_e32 v0, s26, v29
	v_mul_lo_u32 v0, v0, s5
	v_lshl_add_u32 v4, v19, 3, v0
	v_lshlrev_b32_e32 v0, 9, v29
	v_lshl_or_b32 v0, s4, 13, v0
	v_lshl_add_u64 v[2:3], s[12:13], 0, v[0:1]
	v_mov_b32_e32 v19, v1
	v_lshl_add_u64 v[14:15], v[2:3], 0, v[18:19]
	s_waitcnt lgkmcnt(0)
	s_barrier
	global_load_dwordx4 v[6:9], v[14:15], off
	global_load_dwordx4 v[10:13], v[14:15], off offset:64
	v_lshl_add_u32 v0, v4, 1, s18
	ds_read_b128 v[2:5], v0
	v_readlane_b32 s12, v250, 53
	v_readlane_b32 s13, v250, 54
	s_mov_b32 s5, s13
	v_writelane_b32 v250, s4, 53
	s_waitcnt vmcnt(1) lgkmcnt(0)
	v_mfma_f32_16x16x32_bf16 v[2:5], v[2:5], v[6:9], 0
	ds_read_b128 v[6:9], v0 offset:64
	v_writelane_b32 v250, s5, 54
	s_waitcnt vmcnt(0) lgkmcnt(0)
	v_mfma_f32_16x16x32_bf16 v[2:5], v[6:9], v[10:13], v[2:5]
	global_load_dwordx4 v[10:13], v[14:15], off offset:128
	ds_read_b128 v[6:9], v0 offset:128
	s_waitcnt vmcnt(0) lgkmcnt(0)
	v_mfma_f32_16x16x32_bf16 v[2:5], v[6:9], v[10:13], v[2:5]
	global_load_dwordx4 v[10:13], v[14:15], off offset:192
	ds_read_b128 v[6:9], v0 offset:192
	s_waitcnt vmcnt(0) lgkmcnt(0)
	v_mfma_f32_16x16x32_bf16 v[2:5], v[6:9], v[10:13], v[2:5]
	global_load_dwordx4 v[10:13], v[14:15], off offset:256
	ds_read_b128 v[6:9], v0 offset:256
	s_waitcnt vmcnt(0) lgkmcnt(0)
	v_mfma_f32_16x16x32_bf16 v[2:5], v[6:9], v[10:13], v[2:5]
	global_load_dwordx4 v[10:13], v[14:15], off offset:320
	ds_read_b128 v[6:9], v0 offset:320
	s_waitcnt vmcnt(0) lgkmcnt(0)
	v_mfma_f32_16x16x32_bf16 v[2:5], v[6:9], v[10:13], v[2:5]
	global_load_dwordx4 v[10:13], v[14:15], off offset:384
	ds_read_b128 v[6:9], v0 offset:384
	s_waitcnt vmcnt(0) lgkmcnt(0)
	v_mfma_f32_16x16x32_bf16 v[2:5], v[6:9], v[10:13], v[2:5]
	global_load_dwordx4 v[10:13], v[14:15], off offset:448
	ds_read_b128 v[6:9], v0 offset:448
	v_mov_b32_e32 v0, s34
	s_mov_b64 s[34:35], -1
	v_readfirstlane_b32 s12, v0
	s_bfe_i64 s[12:13], s[12:13], 0x80000
	s_lshl_b64 s[30:31], s[12:13], 17
	s_waitcnt vmcnt(0) lgkmcnt(0)
	v_mfma_f32_16x16x32_bf16 v[2:5], v[6:9], v[10:13], v[2:5]
	s_cbranch_vccz .LBB0_798
	v_readlane_b32 s5, v249, 42
	s_add_u32 s10, s5, s30
	v_readlane_b32 s5, v249, 43
	v_lshlrev_b32_e32 v0, 11, v29
	s_addc_u32 s11, s5, s31
	v_lshl_or_b32 v0, s4, 15, v0
	v_lshl_add_u64 v[8:9], s[10:11], 0, v[0:1]
	s_ashr_i32 s29, s28, 31
	v_lshl_add_u64 v[8:9], s[28:29], 1, v[8:9]
	s_ashr_i32 s27, s26, 31
	v_lshl_add_u64 v[8:9], s[26:27], 1, v[8:9]
	v_lshlrev_b32_e32 v0, 1, v26
	v_cvt_pk_bf16_f32 v6, v2, v3
	v_cvt_pk_bf16_f32 v7, v4, v5
	v_lshl_add_u64 v[8:9], v[8:9], 0, v[0:1]
	global_store_dwordx2 v[8:9], v[6:7], off
	s_mov_b64 s[34:35], 0
